# streamer counts retuned for the new decode loop: P2 104 workgroups (13 groups of 8), P3 88 workgroups
# speedup vs baseline: 1.0276x; 1.0077x over previous
; __device__ __forceinline__ void sb_decode_stream(Frame& F, unsigned* qctr, int base, int limit) {
;     const float* CK = kin(2); const float* CV = kin(3); const int* PT = (const int*)kin(4);
;     int lane = F.lane; asm volatile("" : "+v"(lane));
;     const int half = lane >> 5, l32 = lane & 31;
;     const float k1 = SB_SCALE * 1.4426950408889634f;
;     const size_t lo = (size_t)half * (NH * HD) + 4 * l32;
;     int it;
;     { const unsigned v = __hip_atomic_fetch_add(qctr, 1u, __ATOMIC_RELAXED, __HIP_MEMORY_SCOPE_AGENT);
;       it = (int)(__builtin_amdgcn_readfirstlane(v) >> 6); if (it >= limit) return; it += base; }
; __global__ void __launch_bounds__(NWAVES * 64, 2) hymba_fwd(Args args) {
;     ...
;         const bool streamer = (F.bid % 3) == 0 && F.bid < 252;
;         if (streamer) sb_decode_stream(F, F.ctl + CW_QUEUE, 0, DEC_Q2);
.LBB0_1119:
	s_cmp_lt_i32 s84, 3
	s_cselect_b64 s[2:3], -1, 0
	s_cmp_gt_i32 s85, 2
	s_cselect_b64 s[4:5], -1, 0
	s_and_b64 s[2:3], s[2:3], s[4:5]
	s_andn2_b64 vcc, exec, s[2:3]
	s_cbranch_vccnz .LBB0_1376
	s_lshr_b32 s2, s96, 3
	s_mov_b32 s3, 0x4a5294a5
	s_lshr_b32 s3, s3, s2
	s_and_b32 s3, s3, 1
	s_cmp_eq_u32 s3, 1
	s_cselect_b64 s[42:43], -1, 0
	s_add_u32 s40, s26, 0x1000
	s_addc_u32 s41, s27, 0
	s_add_u32 s38, s26, 0x2ff18000
	s_addc_u32 s39, s27, 0
	s_add_u32 s3, s26, 0x2ff70400
	s_addc_u32 s4, s27, 0
	s_and_b64 vcc, exec, s[42:43]
	s_cbranch_vccz .LBB0_1132
	s_load_dwordx2 s[50:51], s[0:1], 0x10
	s_load_dwordx2 s[52:53], s[0:1], 0x18
	s_load_dwordx2 s[54:55], s[0:1], 0x20
	s_load_dwordx2 s[56:57], s[0:1], 0x60
	s_add_u32 s58, s26, 0x1000
	s_addc_u32 s59, s27, 0
	s_add_u32 s60, s26, 0x2ff18000
	s_addc_u32 s61, s27, 0
	s_add_u32 s62, s26, 0x2ff70400
	s_addc_u32 s63, s27, 0
	s_mov_b32 s76, 0xcccccccc
	s_mov_b32 s77, 0xcccccccc
	s_mov_b32 s78, 0xaaaaaaaa
	s_mov_b32 s79, 0xaaaaaaaa
	v_and_b32_e32 v193, 31, v199
	v_lshrrev_b32_e32 v188, 5, v199
	v_lshlrev_b32_e32 v193, 4, v193
	v_lshl_add_u32 v187, v188, 12, v193
	v_lshlrev_b32_e32 v188, 7, v188
	v_mov_b32_e32 v189, 0
	v_mov_b32_e32 v190, 64
	v_mov_b32_e32 v190, 0x200
	s_mov_b32 s37, 0x251e0
	s_cmp_eq_u32 s94, 0
	s_cbranch_scc0 .Ldqa_pro
	s_mov_b64 exec, 1
	global_atomic_add v191, v189, v190, s[58:59] sc0
	s_mov_b64 exec, -1

; __device__ __forceinline__ void p2_mixers(Frame& F, unsigned* qctr) {
;     ...
;     const bool streamer = (F.bid >= NB * NH) && (((F.bid >> 3) - 2) % 5 < 2);
;     if (streamer) sb_decode_stream(F, qctr + 64, DEC_Q2, DEC_ITEMS - DEC_Q2);
.LBB0_1408:
	s_lshr_b32 s2, s96, 3
	s_mov_b32 s3, 0x8c6318c
	s_lshr_b32 s3, s3, s2
	s_and_b32 s3, s3, 1
	s_cmp_eq_u32 s3, 0
	s_cselect_b64 s[6:7], -1, 0
	s_add_u32 s38, s26, 0x1100
	s_addc_u32 s39, s27, 0
	s_add_u32 s3, s26, 0x2ff18000
	s_addc_u32 s4, s27, 0
	s_add_u32 s5, s26, 0x2ff70400
	s_addc_u32 s23, s27, 0
	s_or_b64 s[6:7], s[10:11], s[6:7]
	s_andn2_b64 vcc, exec, s[6:7]
	s_cbranch_vccz .LBB0_1420
	s_load_dwordx2 s[50:51], s[0:1], 0x10
	s_load_dwordx2 s[52:53], s[0:1], 0x18
	s_load_dwordx2 s[54:55], s[0:1], 0x20
	s_load_dwordx2 s[56:57], s[0:1], 0x60
	s_add_u32 s58, s26, 0x1100
	s_addc_u32 s59, s27, 0
	s_add_u32 s60, s26, 0x2ff18000
	s_addc_u32 s61, s27, 0
	s_add_u32 s62, s26, 0x2ff70400
	s_addc_u32 s63, s27, 0
	s_mov_b32 s76, 0xcccccccc
	s_mov_b32 s77, 0xcccccccc
	s_mov_b32 s78, 0xaaaaaaaa
	s_mov_b32 s79, 0xaaaaaaaa
	v_and_b32_e32 v193, 31, v199
	v_lshrrev_b32_e32 v188, 5, v199
	v_lshlrev_b32_e32 v193, 4, v193
	v_lshl_add_u32 v187, v188, 12, v193
	v_lshlrev_b32_e32 v188, 7, v188
	v_mov_b32_e32 v189, 0
	v_mov_b32_e32 v190, 64
	v_mov_b32_e32 v190, 0x200
	s_mov_b32 s37, 0x251e0
	s_cmp_eq_u32 s94, 0
	s_cbranch_scc0 .Ldqc_pro
	s_mov_b64 exec, 1
	global_atomic_add v191, v189, v190, s[58:59] sc0
	s_mov_b64 exec, -1
